# v63 + grid barrier: waiting workgroups poll the release generation less often (s_sleep 10 between polls) so the arrival / release atomics are not queued behind polls
# baseline (speedup 1.0000x reference)
; __device__ __forceinline__ unsigned xb_ld(unsigned* p)              { return __hip_atomic_load(p, __ATOMIC_RELAXED, __HIP_MEMORY_SCOPE_AGENT); }
; #define XB_SPIN(cond, bar) do { unsigned _sp = 0; while (cond) { __builtin_amdgcn_s_sleep(1); \
;     if ((++_sp & 255u) == 0u) { if (xb_ld(&(bar)[XB_TMO])) break; if (_sp > XB_SPIN_CAP) { atomicAdd(&(bar)[XB_TMO], 1u); break; } } } } while (0)
; __device__ __forceinline__ void xcd_barrier(const XcdBarrier& b) {
;     ...
;             XB_SPIN(xb_ld(&bar[XB_XGEN(b.x)]) == gen, bar);
.LBB0_220:
	s_and_b32 s5, s4, 0xff
	s_mov_b64 s[20:21], -1
	s_cmp_lg_u32 s5, 0
	s_mov_b64 s[24:25], -1
	s_sleep 10
	s_cbranch_scc0 .LBB0_223
	s_and_b64 vcc, exec, s[24:25]
	s_cbranch_vccz .LBB0_219

; __device__ __forceinline__ unsigned xb_ld(unsigned* p)              { return __hip_atomic_load(p, __ATOMIC_RELAXED, __HIP_MEMORY_SCOPE_AGENT); }
; #define XB_SPIN(cond, bar) do { unsigned _sp = 0; while (cond) { __builtin_amdgcn_s_sleep(1); \
;     if ((++_sp & 255u) == 0u) { if (xb_ld(&(bar)[XB_TMO])) break; if (_sp > XB_SPIN_CAP) { atomicAdd(&(bar)[XB_TMO], 1u); break; } } } } while (0)
; __device__ __forceinline__ void xcd_barrier(const XcdBarrier& b) {
;     ...
;             XB_SPIN(xb_ld(&bar[XB_XGEN(b.x)]) == gen, bar);
.LBB0_314:
	s_and_b32 s4, s2, 0xff
	s_mov_b64 s[20:21], -1
	s_cmp_lg_u32 s4, 0
	s_mov_b64 s[24:25], -1
	s_sleep 10
	s_cbranch_scc0 .LBB0_317
	s_and_b64 vcc, exec, s[24:25]
	s_cbranch_vccz .LBB0_313

; __device__ __forceinline__ unsigned xb_ld(unsigned* p)              { return __hip_atomic_load(p, __ATOMIC_RELAXED, __HIP_MEMORY_SCOPE_AGENT); }
; #define XB_SPIN(cond, bar) do { unsigned _sp = 0; while (cond) { __builtin_amdgcn_s_sleep(1); \
;     if ((++_sp & 255u) == 0u) { if (xb_ld(&(bar)[XB_TMO])) break; if (_sp > XB_SPIN_CAP) { atomicAdd(&(bar)[XB_TMO], 1u); break; } } } } while (0)
; __device__ __forceinline__ void xcd_barrier(const XcdBarrier& b) {
;     ...
;             XB_SPIN(xb_ld(&bar[XB_XGEN(b.x)]) == gen, bar);
.LBB0_577:
	s_and_b32 s5, s4, 0xff
	s_mov_b64 s[18:19], -1
	s_cmp_lg_u32 s5, 0
	s_mov_b64 s[22:23], -1
	s_sleep 10
	s_cbranch_scc0 .LBB0_580
	s_and_b64 vcc, exec, s[22:23]
	s_cbranch_vccz .LBB0_576

; __device__ __forceinline__ unsigned xb_ld(unsigned* p)              { return __hip_atomic_load(p, __ATOMIC_RELAXED, __HIP_MEMORY_SCOPE_AGENT); }
; #define XB_SPIN(cond, bar) do { unsigned _sp = 0; while (cond) { __builtin_amdgcn_s_sleep(1); \
;     if ((++_sp & 255u) == 0u) { if (xb_ld(&(bar)[XB_TMO])) break; if (_sp > XB_SPIN_CAP) { atomicAdd(&(bar)[XB_TMO], 1u); break; } } } } while (0)
; __device__ __forceinline__ void xcd_barrier(const XcdBarrier& b) {
;     ...
;             XB_SPIN(xb_ld(&bar[XB_XGEN(b.x)]) == gen, bar);
.LBB0_1282:
	s_and_b32 s20, s24, 0xff
	s_mov_b64 s[18:19], -1
	s_cmp_lg_u32 s20, 0
	s_mov_b64 s[22:23], -1
	s_sleep 10
	s_cbranch_scc0 .LBB0_1285
	s_and_b64 vcc, exec, s[22:23]
	s_cbranch_vccz .LBB0_1281

; __device__ __forceinline__ unsigned xb_ld(unsigned* p)              { return __hip_atomic_load(p, __ATOMIC_RELAXED, __HIP_MEMORY_SCOPE_AGENT); }
; #define XB_SPIN(cond, bar) do { unsigned _sp = 0; while (cond) { __builtin_amdgcn_s_sleep(1); \
;     if ((++_sp & 255u) == 0u) { if (xb_ld(&(bar)[XB_TMO])) break; if (_sp > XB_SPIN_CAP) { atomicAdd(&(bar)[XB_TMO], 1u); break; } } } } while (0)
; __device__ __forceinline__ void xcd_barrier(const XcdBarrier& b) {
;     ...
;             XB_SPIN(xb_ld(&bar[XB_XGEN(b.x)]) == gen, bar);
.LBB0_1406:
	s_and_b32 s20, s2, 0xff
	s_mov_b64 s[18:19], -1
	s_cmp_lg_u32 s20, 0
	s_mov_b64 s[22:23], -1
	s_sleep 10
	s_cbranch_scc0 .LBB0_1409
	s_and_b64 vcc, exec, s[22:23]
	s_cbranch_vccz .LBB0_1405
